# nt hint also on the MLP-up result stores (ACT, 285 MB)
# baseline (speedup 1.0000x reference)
.LBB0_1143:
	v_lshl_add_u32 v144, s1, 8, v140
	v_max_f32_e32 v120, v120, v120
	v_ashrrev_i32_e32 v145, 31, v144
	v_max_f32_e32 v120, 0, v120
	v_max_f32_e32 v121, v121, v121
	v_max_f32_e32 v122, v122, v122
	v_lshl_or_b32 v138, s0, 8, v142
	v_lshlrev_b64 v[146:147], 14, v[144:145]
	v_mul_f32_e32 v145, v120, v120
	v_max_f32_e32 v120, v125, v125
	v_max_f32_e32 v121, 0, v121
	v_max_f32_e32 v122, 0, v122
	v_ashrrev_i32_e32 v139, 31, v138
	v_max_f32_e32 v124, v124, v124
	v_max_f32_e32 v120, 0, v120
	v_mul_f32_e32 v125, v121, v121
	v_max_f32_e32 v121, v126, v126
	v_mul_f32_e32 v126, v122, v122
	v_max_f32_e32 v122, v127, v127
	v_max_f32_e32 v123, v123, v123
	v_lshl_add_u64 v[146:147], s[42:43], 0, v[146:147]
	v_lshlrev_b64 v[148:149], 1, v[138:139]
	v_max_f32_e32 v124, 0, v124
	v_mul_f32_e32 v120, v120, v120
	v_max_f32_e32 v121, 0, v121
	v_max_f32_e32 v122, 0, v122
	v_max_f32_e32 v123, 0, v123
	v_max_f32_e32 v112, v112, v112
	v_lshl_add_u64 v[138:139], v[146:147], 0, v[148:149]
	v_mul_f32_e32 v124, v124, v124
	v_mul_f32_e32 v121, v121, v121
	v_mul_f32_e32 v122, v122, v122
	v_mul_f32_e32 v123, v123, v123
	v_cvt_pk_bf16_f32 v120, v124, v120
	v_max_f32_e32 v112, 0, v112
	v_max_f32_e32 v113, v113, v113
	v_max_f32_e32 v114, v114, v114
	v_cvt_pk_bf16_f32 v121, v121, v122
	v_cvt_pk_bf16_f32 v122, v145, v125
	v_cvt_pk_bf16_f32 v123, v126, v123
	global_store_dwordx4 v[138:139], v[120:123], off nt
	v_max_f32_e32 v113, 0, v113
	v_max_f32_e32 v114, 0, v114
	v_mul_f32_e32 v120, v112, v112
	v_max_f32_e32 v112, v117, v117
	v_max_f32_e32 v116, v116, v116
	v_max_f32_e32 v112, 0, v112
	v_mul_f32_e32 v117, v113, v113
	v_max_f32_e32 v113, v118, v118
	v_mul_f32_e32 v118, v114, v114
	v_max_f32_e32 v114, v119, v119
	v_max_f32_e32 v115, v115, v115
	v_max_f32_e32 v116, 0, v116
	v_mul_f32_e32 v112, v112, v112
	v_max_f32_e32 v113, 0, v113
	v_max_f32_e32 v114, 0, v114
	v_max_f32_e32 v115, 0, v115
	v_mul_f32_e32 v116, v116, v116
	v_mul_f32_e32 v113, v113, v113
	v_mul_f32_e32 v114, v114, v114
	v_mul_f32_e32 v115, v115, v115
	v_cvt_pk_bf16_f32 v112, v116, v112
	v_max_f32_e32 v104, v104, v104
	v_cvt_pk_bf16_f32 v113, v113, v114
	v_cvt_pk_bf16_f32 v114, v120, v117
	v_cvt_pk_bf16_f32 v115, v118, v115
	global_store_dwordx4 v[138:139], v[112:115], off offset:256 nt
	v_max_f32_e32 v104, 0, v104
	v_max_f32_e32 v105, v105, v105
	v_or_b32_e32 v112, 16, v144
	v_max_f32_e32 v106, v106, v106
	v_ashrrev_i32_e32 v113, 31, v112
	v_mul_f32_e32 v114, v104, v104
	v_max_f32_e32 v104, v109, v109
	v_max_f32_e32 v105, 0, v105
	v_max_f32_e32 v106, 0, v106
	v_lshlrev_b64 v[112:113], 14, v[112:113]
	v_max_f32_e32 v108, v108, v108
	v_max_f32_e32 v104, 0, v104
	v_mul_f32_e32 v109, v105, v105
	v_max_f32_e32 v105, v110, v110
	v_mul_f32_e32 v110, v106, v106
	v_max_f32_e32 v106, v111, v111
	v_max_f32_e32 v107, v107, v107
	v_lshl_add_u64 v[112:113], s[42:43], 0, v[112:113]
	v_max_f32_e32 v108, 0, v108
	v_mul_f32_e32 v104, v104, v104
	v_max_f32_e32 v105, 0, v105
	v_max_f32_e32 v106, 0, v106
	v_max_f32_e32 v107, 0, v107
	v_max_f32_e32 v96, v96, v96
	v_lshl_add_u64 v[112:113], v[112:113], 0, v[148:149]
	v_mul_f32_e32 v108, v108, v108
	v_mul_f32_e32 v105, v105, v105
	v_mul_f32_e32 v106, v106, v106
	v_mul_f32_e32 v107, v107, v107
	v_cvt_pk_bf16_f32 v104, v108, v104
	v_max_f32_e32 v96, 0, v96
	v_max_f32_e32 v97, v97, v97
	v_max_f32_e32 v98, v98, v98
	v_cvt_pk_bf16_f32 v105, v105, v106
	v_cvt_pk_bf16_f32 v106, v114, v109
	v_cvt_pk_bf16_f32 v107, v110, v107
	global_store_dwordx4 v[112:113], v[104:107], off nt
	v_max_f32_e32 v97, 0, v97
	v_max_f32_e32 v98, 0, v98
	v_mul_f32_e32 v104, v96, v96
	v_max_f32_e32 v96, v101, v101
	v_max_f32_e32 v100, v100, v100
	v_max_f32_e32 v96, 0, v96
	v_mul_f32_e32 v101, v97, v97
	v_max_f32_e32 v97, v102, v102
	v_mul_f32_e32 v102, v98, v98
	v_max_f32_e32 v98, v103, v103
	v_max_f32_e32 v99, v99, v99
	v_max_f32_e32 v100, 0, v100
	v_mul_f32_e32 v96, v96, v96
	v_max_f32_e32 v97, 0, v97
	v_max_f32_e32 v98, 0, v98
	v_max_f32_e32 v99, 0, v99
	v_mul_f32_e32 v100, v100, v100
	v_mul_f32_e32 v97, v97, v97
	v_mul_f32_e32 v98, v98, v98
	v_mul_f32_e32 v99, v99, v99
	v_cvt_pk_bf16_f32 v96, v100, v96
	v_max_f32_e32 v88, v88, v88
	v_cvt_pk_bf16_f32 v97, v97, v98
	v_cvt_pk_bf16_f32 v98, v104, v101
	v_cvt_pk_bf16_f32 v99, v102, v99
	global_store_dwordx4 v[112:113], v[96:99], off offset:256 nt
	v_max_f32_e32 v88, 0, v88
	v_max_f32_e32 v89, v89, v89
	v_or_b32_e32 v96, 32, v144
	v_max_f32_e32 v90, v90, v90
	v_ashrrev_i32_e32 v97, 31, v96
	v_mul_f32_e32 v98, v88, v88
	v_max_f32_e32 v88, v93, v93
	v_max_f32_e32 v89, 0, v89
	v_max_f32_e32 v90, 0, v90
	v_lshlrev_b64 v[96:97], 14, v[96:97]
	v_max_f32_e32 v92, v92, v92
	v_max_f32_e32 v88, 0, v88
	v_mul_f32_e32 v93, v89, v89
	v_max_f32_e32 v89, v94, v94
	v_mul_f32_e32 v94, v90, v90
	v_max_f32_e32 v90, v95, v95
	v_max_f32_e32 v91, v91, v91
	v_lshl_add_u64 v[96:97], s[42:43], 0, v[96:97]
	v_max_f32_e32 v92, 0, v92
	v_mul_f32_e32 v88, v88, v88
	v_max_f32_e32 v89, 0, v89
	v_max_f32_e32 v90, 0, v90
	v_max_f32_e32 v91, 0, v91
	v_max_f32_e32 v80, v80, v80
	v_lshl_add_u64 v[96:97], v[96:97], 0, v[148:149]
	v_mul_f32_e32 v92, v92, v92
	v_mul_f32_e32 v89, v89, v89
	v_mul_f32_e32 v90, v90, v90
	v_mul_f32_e32 v91, v91, v91
	v_cvt_pk_bf16_f32 v88, v92, v88
	v_max_f32_e32 v80, 0, v80
	v_max_f32_e32 v81, v81, v81
	v_max_f32_e32 v82, v82, v82
	v_cvt_pk_bf16_f32 v89, v89, v90
	v_cvt_pk_bf16_f32 v90, v98, v93
	v_cvt_pk_bf16_f32 v91, v94, v91
	global_store_dwordx4 v[96:97], v[88:91], off nt
	v_max_f32_e32 v81, 0, v81
	v_max_f32_e32 v82, 0, v82
	v_mul_f32_e32 v88, v80, v80
	v_max_f32_e32 v80, v85, v85
	v_max_f32_e32 v84, v84, v84
	v_max_f32_e32 v80, 0, v80
	v_mul_f32_e32 v85, v81, v81
	v_max_f32_e32 v81, v86, v86
	v_mul_f32_e32 v86, v82, v82
	v_max_f32_e32 v82, v87, v87
	v_max_f32_e32 v83, v83, v83
	v_max_f32_e32 v84, 0, v84
	v_mul_f32_e32 v80, v80, v80
	v_max_f32_e32 v81, 0, v81
	v_max_f32_e32 v82, 0, v82
	v_max_f32_e32 v83, 0, v83
	v_mul_f32_e32 v84, v84, v84
	v_mul_f32_e32 v81, v81, v81
	v_mul_f32_e32 v82, v82, v82
	v_mul_f32_e32 v83, v83, v83
	v_cvt_pk_bf16_f32 v80, v84, v80
	v_max_f32_e32 v72, v72, v72
	v_cvt_pk_bf16_f32 v81, v81, v82
	v_cvt_pk_bf16_f32 v82, v88, v85
	v_cvt_pk_bf16_f32 v83, v86, v83
	global_store_dwordx4 v[96:97], v[80:83], off offset:256 nt
	v_max_f32_e32 v72, 0, v72
	v_max_f32_e32 v73, v73, v73
	v_or_b32_e32 v80, 48, v144
	v_max_f32_e32 v74, v74, v74
	v_ashrrev_i32_e32 v81, 31, v80
	v_mul_f32_e32 v82, v72, v72
	v_max_f32_e32 v72, v77, v77
	v_max_f32_e32 v73, 0, v73
	v_max_f32_e32 v74, 0, v74
	v_lshlrev_b64 v[80:81], 14, v[80:81]
	v_max_f32_e32 v76, v76, v76
	v_max_f32_e32 v72, 0, v72
	v_mul_f32_e32 v77, v73, v73
	v_max_f32_e32 v73, v78, v78
	v_mul_f32_e32 v78, v74, v74
	v_max_f32_e32 v74, v79, v79
	v_max_f32_e32 v75, v75, v75
	v_lshl_add_u64 v[80:81], s[42:43], 0, v[80:81]
	v_max_f32_e32 v76, 0, v76
	v_mul_f32_e32 v72, v72, v72
	v_max_f32_e32 v73, 0, v73
	v_max_f32_e32 v74, 0, v74
	v_max_f32_e32 v75, 0, v75
	v_max_f32_e32 v64, v64, v64
	v_max_f32_e32 v65, v65, v65
	v_max_f32_e32 v66, v66, v66
	v_lshl_add_u64 v[80:81], v[80:81], 0, v[148:149]
	v_mul_f32_e32 v76, v76, v76
	v_mul_f32_e32 v73, v73, v73
	v_mul_f32_e32 v74, v74, v74
	v_mul_f32_e32 v75, v75, v75
	v_cvt_pk_bf16_f32 v72, v76, v72
	v_max_f32_e32 v64, 0, v64
	v_max_f32_e32 v65, 0, v65
	v_max_f32_e32 v66, 0, v66
	v_cvt_pk_bf16_f32 v73, v73, v74
	v_cvt_pk_bf16_f32 v74, v82, v77
	v_cvt_pk_bf16_f32 v75, v78, v75
	global_store_dwordx4 v[80:81], v[72:75], off nt
	v_max_f32_e32 v68, v68, v68
	v_max_f32_e32 v67, v67, v67
	v_mul_f32_e32 v72, v64, v64
	v_max_f32_e32 v64, v69, v69
	v_mul_f32_e32 v69, v65, v65
	v_max_f32_e32 v65, v70, v70
	v_mul_f32_e32 v70, v66, v66
	v_max_f32_e32 v66, v71, v71
	v_max_f32_e32 v64, 0, v64
	v_max_f32_e32 v65, 0, v65
	v_max_f32_e32 v66, 0, v66
	v_max_f32_e32 v68, 0, v68
	v_mul_f32_e32 v64, v64, v64
	v_mul_f32_e32 v65, v65, v65
	v_mul_f32_e32 v66, v66, v66
	v_max_f32_e32 v67, 0, v67
	v_max_f32_e32 v56, v56, v56
	v_mul_f32_e32 v68, v68, v68
	v_mul_f32_e32 v67, v67, v67
	v_cvt_pk_bf16_f32 v64, v68, v64
	v_cvt_pk_bf16_f32 v65, v65, v66
	v_cvt_pk_bf16_f32 v66, v72, v69
	v_max_f32_e32 v56, 0, v56
	v_max_f32_e32 v57, v57, v57
	v_max_f32_e32 v58, v58, v58
	v_cvt_pk_bf16_f32 v67, v70, v67
	global_store_dwordx4 v[80:81], v[64:67], off offset:256 nt
	v_max_f32_e32 v60, v60, v60
	v_max_f32_e32 v57, 0, v57
	v_mul_f32_e32 v66, v56, v56
	v_max_f32_e32 v56, v61, v61
	v_max_f32_e32 v58, 0, v58
	s_mov_b64 s[0:1], 0x200000
	v_max_f32_e32 v60, 0, v60
	v_max_f32_e32 v56, 0, v56
	v_mul_f32_e32 v61, v57, v57
	v_max_f32_e32 v57, v62, v62
	v_mul_f32_e32 v62, v58, v58
	v_max_f32_e32 v58, v63, v63
	v_lshl_add_u64 v[64:65], v[138:139], 0, s[0:1]
	v_mul_f32_e32 v60, v60, v60
	v_mul_f32_e32 v56, v56, v56
	v_max_f32_e32 v57, 0, v57
	v_max_f32_e32 v58, 0, v58
	v_max_f32_e32 v59, v59, v59
	s_mov_b32 s0, 0x200000
	v_mul_f32_e32 v57, v57, v57
	v_mul_f32_e32 v58, v58, v58
	v_max_f32_e32 v59, 0, v59
	v_cvt_pk_bf16_f32 v56, v60, v56
	v_add_co_u32_e32 v60, vcc, s0, v138
	v_max_f32_e32 v48, v48, v48
	v_max_f32_e32 v49, v49, v49
	v_max_f32_e32 v50, v50, v50
	v_mul_f32_e32 v59, v59, v59
	v_cvt_pk_bf16_f32 v57, v57, v58
	v_cvt_pk_bf16_f32 v58, v66, v61
	v_addc_co_u32_e32 v61, vcc, 0, v139, vcc
	v_max_f32_e32 v48, 0, v48
	v_max_f32_e32 v49, 0, v49
	v_max_f32_e32 v50, 0, v50
	v_cvt_pk_bf16_f32 v59, v62, v59
	global_store_dwordx4 v[60:61], v[56:59], off nt
	v_max_f32_e32 v52, v52, v52
	v_max_f32_e32 v51, v51, v51
	v_mul_f32_e32 v56, v48, v48
	v_max_f32_e32 v48, v53, v53
	v_mul_f32_e32 v53, v49, v49
	v_max_f32_e32 v49, v54, v54
	v_mul_f32_e32 v54, v50, v50
	v_max_f32_e32 v50, v55, v55
	v_max_f32_e32 v48, 0, v48
	v_max_f32_e32 v49, 0, v49
	v_max_f32_e32 v50, 0, v50
	v_max_f32_e32 v52, 0, v52
	v_mul_f32_e32 v48, v48, v48
	v_mul_f32_e32 v49, v49, v49
	v_mul_f32_e32 v50, v50, v50
	v_max_f32_e32 v51, 0, v51
	v_max_f32_e32 v40, v40, v40
	v_mul_f32_e32 v52, v52, v52
	v_mul_f32_e32 v51, v51, v51
	v_cvt_pk_bf16_f32 v48, v52, v48
	v_cvt_pk_bf16_f32 v49, v49, v50
	v_cvt_pk_bf16_f32 v50, v56, v53
	v_max_f32_e32 v40, 0, v40
	v_max_f32_e32 v41, v41, v41
	v_max_f32_e32 v42, v42, v42
	v_cvt_pk_bf16_f32 v51, v54, v51
	global_store_dwordx4 v[64:65], v[48:51], off offset:256 nt
	v_max_f32_e32 v44, v44, v44
	v_max_f32_e32 v41, 0, v41
	v_mul_f32_e32 v50, v40, v40
	v_max_f32_e32 v40, v45, v45
	v_max_f32_e32 v42, 0, v42
	s_mov_b64 s[0:1], 0x240000
	v_max_f32_e32 v44, 0, v44
	v_max_f32_e32 v40, 0, v40
	v_mul_f32_e32 v45, v41, v41
	v_max_f32_e32 v41, v46, v46
	v_mul_f32_e32 v46, v42, v42
	v_max_f32_e32 v42, v47, v47
	v_lshl_add_u64 v[48:49], v[138:139], 0, s[0:1]
	v_mul_f32_e32 v44, v44, v44
	v_mul_f32_e32 v40, v40, v40
	v_max_f32_e32 v41, 0, v41
	v_max_f32_e32 v42, 0, v42
	v_max_f32_e32 v43, v43, v43
	s_mov_b32 s0, 0x240000
	v_mul_f32_e32 v41, v41, v41
	v_mul_f32_e32 v42, v42, v42
	v_max_f32_e32 v43, 0, v43
	v_cvt_pk_bf16_f32 v40, v44, v40
	v_add_co_u32_e32 v44, vcc, s0, v138
	v_max_f32_e32 v32, v32, v32
	v_max_f32_e32 v33, v33, v33
	v_max_f32_e32 v34, v34, v34
	v_mul_f32_e32 v43, v43, v43
	v_cvt_pk_bf16_f32 v41, v41, v42
	v_cvt_pk_bf16_f32 v42, v50, v45
	v_addc_co_u32_e32 v45, vcc, 0, v139, vcc
	v_max_f32_e32 v32, 0, v32
	v_max_f32_e32 v33, 0, v33
	v_max_f32_e32 v34, 0, v34
	v_cvt_pk_bf16_f32 v43, v46, v43
	global_store_dwordx4 v[44:45], v[40:43], off nt
	v_max_f32_e32 v36, v36, v36
	v_max_f32_e32 v35, v35, v35
	v_mul_f32_e32 v40, v32, v32
	v_max_f32_e32 v32, v37, v37
	v_mul_f32_e32 v37, v33, v33
	v_max_f32_e32 v33, v38, v38
	v_mul_f32_e32 v38, v34, v34
	v_max_f32_e32 v34, v39, v39
	v_max_f32_e32 v32, 0, v32
	v_max_f32_e32 v33, 0, v33
	v_max_f32_e32 v34, 0, v34
	v_max_f32_e32 v36, 0, v36
	v_mul_f32_e32 v32, v32, v32
	v_mul_f32_e32 v33, v33, v33
	v_mul_f32_e32 v34, v34, v34
	v_max_f32_e32 v35, 0, v35
	v_max_f32_e32 v24, v24, v24
	v_mul_f32_e32 v36, v36, v36
	v_mul_f32_e32 v35, v35, v35
	v_cvt_pk_bf16_f32 v32, v36, v32
	v_cvt_pk_bf16_f32 v33, v33, v34
	v_cvt_pk_bf16_f32 v34, v40, v37
	v_max_f32_e32 v24, 0, v24
	v_max_f32_e32 v25, v25, v25
	v_max_f32_e32 v26, v26, v26
	v_cvt_pk_bf16_f32 v35, v38, v35
	global_store_dwordx4 v[48:49], v[32:35], off offset:256 nt
	v_max_f32_e32 v28, v28, v28
	v_max_f32_e32 v25, 0, v25
	v_mul_f32_e32 v34, v24, v24
	v_max_f32_e32 v24, v29, v29
	v_max_f32_e32 v26, 0, v26
	s_mov_b64 s[0:1], 0x280000
	v_max_f32_e32 v28, 0, v28
	v_max_f32_e32 v24, 0, v24
	v_mul_f32_e32 v29, v25, v25
	v_max_f32_e32 v25, v30, v30
	v_mul_f32_e32 v30, v26, v26
	v_max_f32_e32 v26, v31, v31
	v_lshl_add_u64 v[32:33], v[138:139], 0, s[0:1]
	v_mul_f32_e32 v28, v28, v28
	v_mul_f32_e32 v24, v24, v24
	v_max_f32_e32 v25, 0, v25
	v_max_f32_e32 v26, 0, v26
	v_max_f32_e32 v27, v27, v27
	s_mov_b32 s0, 0x280000
	v_mul_f32_e32 v25, v25, v25
	v_mul_f32_e32 v26, v26, v26
	v_max_f32_e32 v27, 0, v27
	v_cvt_pk_bf16_f32 v24, v28, v24
	v_add_co_u32_e32 v28, vcc, s0, v138
	v_max_f32_e32 v16, v16, v16
	v_max_f32_e32 v17, v17, v17
	v_max_f32_e32 v18, v18, v18
	v_mul_f32_e32 v27, v27, v27
	v_cvt_pk_bf16_f32 v25, v25, v26
	v_cvt_pk_bf16_f32 v26, v34, v29
	v_addc_co_u32_e32 v29, vcc, 0, v139, vcc
	v_max_f32_e32 v16, 0, v16
	v_max_f32_e32 v17, 0, v17
	v_max_f32_e32 v18, 0, v18
	v_cvt_pk_bf16_f32 v27, v30, v27
	global_store_dwordx4 v[28:29], v[24:27], off nt
	v_max_f32_e32 v20, v20, v20
	v_max_f32_e32 v19, v19, v19
	v_mul_f32_e32 v24, v16, v16
	v_max_f32_e32 v16, v21, v21
	v_mul_f32_e32 v21, v17, v17
	v_max_f32_e32 v17, v22, v22
	v_mul_f32_e32 v22, v18, v18
	v_max_f32_e32 v18, v23, v23
	v_max_f32_e32 v16, 0, v16
	v_max_f32_e32 v17, 0, v17
	v_max_f32_e32 v18, 0, v18
	v_max_f32_e32 v20, 0, v20
	v_mul_f32_e32 v16, v16, v16
	v_mul_f32_e32 v17, v17, v17
	v_mul_f32_e32 v18, v18, v18
	v_max_f32_e32 v19, 0, v19
	v_max_f32_e32 v8, v8, v8
	v_mul_f32_e32 v20, v20, v20
	v_mul_f32_e32 v19, v19, v19
	v_cvt_pk_bf16_f32 v16, v20, v16
	v_cvt_pk_bf16_f32 v17, v17, v18
	v_cvt_pk_bf16_f32 v18, v24, v21
	v_max_f32_e32 v8, 0, v8
	v_max_f32_e32 v9, v9, v9
	v_max_f32_e32 v10, v10, v10
	v_cvt_pk_bf16_f32 v19, v22, v19
	global_store_dwordx4 v[32:33], v[16:19], off offset:256 nt
	v_max_f32_e32 v12, v12, v12
	v_max_f32_e32 v9, 0, v9
	v_mul_f32_e32 v18, v8, v8
	v_max_f32_e32 v8, v13, v13
	v_max_f32_e32 v10, 0, v10
	s_mov_b64 s[0:1], 0x2c0000
	v_max_f32_e32 v12, 0, v12
	v_max_f32_e32 v8, 0, v8
	v_mul_f32_e32 v13, v9, v9
	v_max_f32_e32 v9, v14, v14
	v_mul_f32_e32 v14, v10, v10
	v_max_f32_e32 v10, v15, v15
	v_lshl_add_u64 v[16:17], v[138:139], 0, s[0:1]
	v_mul_f32_e32 v12, v12, v12
	v_mul_f32_e32 v8, v8, v8
	v_max_f32_e32 v9, 0, v9
	v_max_f32_e32 v10, 0, v10
	v_max_f32_e32 v11, v11, v11
	s_mov_b32 s0, 0x2c0000
	v_mul_f32_e32 v9, v9, v9
	v_mul_f32_e32 v10, v10, v10
	v_max_f32_e32 v11, 0, v11
	v_cvt_pk_bf16_f32 v8, v12, v8
	v_add_co_u32_e32 v12, vcc, s0, v138
	v_max_f32_e32 v0, v0, v0
	v_max_f32_e32 v1, v1, v1
	v_max_f32_e32 v2, v2, v2
	v_mul_f32_e32 v11, v11, v11
	v_cvt_pk_bf16_f32 v9, v9, v10
	v_cvt_pk_bf16_f32 v10, v18, v13
	v_addc_co_u32_e32 v13, vcc, 0, v139, vcc
	v_max_f32_e32 v0, 0, v0
	v_max_f32_e32 v1, 0, v1
	v_max_f32_e32 v2, 0, v2
	v_cvt_pk_bf16_f32 v11, v14, v11
	global_store_dwordx4 v[12:13], v[8:11], off nt
	v_max_f32_e32 v3, v3, v3
	v_max_f32_e32 v4, v4, v4
	v_mul_f32_e32 v8, v0, v0
	v_max_f32_e32 v0, v5, v5
	v_mul_f32_e32 v5, v1, v1
	v_max_f32_e32 v1, v6, v6
	v_mul_f32_e32 v6, v2, v2
	v_max_f32_e32 v2, v7, v7
	v_max_f32_e32 v0, 0, v0
	v_max_f32_e32 v1, 0, v1
	v_max_f32_e32 v2, 0, v2
	v_max_f32_e32 v3, 0, v3
	v_max_f32_e32 v4, 0, v4
	v_mul_f32_e32 v0, v0, v0
	v_mul_f32_e32 v1, v1, v1
	v_mul_f32_e32 v2, v2, v2
	v_mul_f32_e32 v3, v3, v3
	s_andn2_b64 vcc, exec, s[30:31]
	s_mov_b64 s[0:1], -1
	v_mul_f32_e32 v4, v4, v4
	v_cvt_pk_bf16_f32 v0, v4, v0
	v_cvt_pk_bf16_f32 v1, v1, v2
	v_cvt_pk_bf16_f32 v2, v8, v5
	v_cvt_pk_bf16_f32 v3, v6, v3
	global_store_dwordx4 v[16:17], v[0:3], off offset:256 nt
	s_cbranch_vccnz .LBB0_1138
	s_andn2_b64 vcc, exec, s[10:11]
	s_cbranch_vccnz .LBB0_1137
	s_barrier
	s_branch .LBB0_1137
